# sample-attn: scores moved from MFMA accumulator to softmax layout by permlane swaps (no LDS store/load round trip)
# speedup vs baseline: 1.0086x; 1.0061x over previous
.LBB0_1867:
	v_add_u32_e32 v204, 0, v216
	v_add_u32_e32 v154, 0x12080, v204
	v_add_u32_e32 v196, 0x120c0, v204
	ds_read_b128 v[154:157], v154
	ds_read_b128 v[196:199], v196
	v_and_or_b32 v200, s50, 48, v183
	v_mad_u32_u24 v205, v200, s77, v185
	v_add_u32_e32 v237, 0x12100, v204
	v_mfma_f32_16x16x32_bf16 v[200:203], v[2:5], v[146:149], 0
	ds_read_b128 v[238:241], v237
	v_mfma_f32_16x16x32_bf16 v[220:223], v[6:9], v[146:149], 0
	v_mfma_f32_16x16x32_bf16 v[224:227], v[10:13], v[146:149], 0
	v_mfma_f32_16x16x32_bf16 v[146:149], v[14:17], v[146:149], 0
	v_mfma_f32_16x16x32_bf16 v[200:203], v[18:21], v[150:153], v[200:203]
	v_mfma_f32_16x16x32_bf16 v[220:223], v[22:25], v[150:153], v[220:223]
	v_mfma_f32_16x16x32_bf16 v[224:227], v[26:29], v[150:153], v[224:227]
	v_mfma_f32_16x16x32_bf16 v[146:149], v[30:33], v[150:153], v[146:149]
	v_add_u32_e32 v150, 0x12140, v204
	ds_read_b128 v[150:153], v150
	s_waitcnt lgkmcnt(2)
	v_mfma_f32_16x16x32_bf16 v[200:203], v[34:37], v[154:157], v[200:203]
	v_mfma_f32_16x16x32_bf16 v[220:223], v[38:41], v[154:157], v[220:223]
	v_mfma_f32_16x16x32_bf16 v[224:227], v[42:45], v[154:157], v[224:227]
	v_mfma_f32_16x16x32_bf16 v[146:149], v[46:49], v[154:157], v[146:149]
	v_add_u32_e32 v154, 0x12180, v204
	ds_read_b128 v[154:157], v154
	v_mfma_f32_16x16x32_bf16 v[200:203], v[50:53], v[196:199], v[200:203]
	v_mfma_f32_16x16x32_bf16 v[220:223], v[54:57], v[196:199], v[220:223]
	v_mfma_f32_16x16x32_bf16 v[224:227], v[58:61], v[196:199], v[224:227]
	v_mfma_f32_16x16x32_bf16 v[146:149], v[62:65], v[196:199], v[146:149]
	v_add_u32_e32 v196, 0x121c0, v204
	ds_read_b128 v[196:199], v196
	s_waitcnt lgkmcnt(3)
	v_mfma_f32_16x16x32_bf16 v[200:203], v[66:69], v[238:241], v[200:203]
	v_mfma_f32_16x16x32_bf16 v[220:223], v[70:73], v[238:241], v[220:223]
	v_mfma_f32_16x16x32_bf16 v[224:227], v[74:77], v[238:241], v[224:227]
	v_mfma_f32_16x16x32_bf16 v[238:241], v[78:81], v[238:241], v[146:149]
	s_nop 2
	ds_read_b128 v[146:149], v205
	s_waitcnt lgkmcnt(3)
	v_mfma_f32_16x16x32_bf16 v[200:203], v[82:85], v[150:153], v[200:203]
	v_mfma_f32_16x16x32_bf16 v[220:223], v[86:89], v[150:153], v[220:223]
	v_mfma_f32_16x16x32_bf16 v[224:227], v[90:93], v[150:153], v[224:227]
	v_mfma_f32_16x16x32_bf16 v[238:241], v[94:97], v[150:153], v[238:241]
	ds_read_b128 v[150:153], v205 offset:64
	s_waitcnt lgkmcnt(3)
	v_mfma_f32_16x16x32_bf16 v[200:203], v[98:101], v[154:157], v[200:203]
	v_mfma_f32_16x16x32_bf16 v[220:223], v[102:105], v[154:157], v[220:223]
	v_mfma_f32_16x16x32_bf16 v[224:227], v[106:109], v[154:157], v[224:227]
	v_mfma_f32_16x16x32_bf16 v[154:157], v[110:113], v[154:157], v[238:241]
	s_waitcnt lgkmcnt(2)
	v_mfma_f32_16x16x32_bf16 v[220:223], v[118:121], v[196:199], v[220:223]
	v_mfma_f32_16x16x32_bf16 v[154:157], v[126:129], v[196:199], v[154:157]
	v_mfma_f32_16x16x32_bf16 v[200:203], v[114:117], v[196:199], v[200:203]
	v_mfma_f32_16x16x32_bf16 v[224:227], v[122:125], v[196:199], v[224:227]
	ds_read_b128 v[196:199], v217
	ds_read_b128 v[242:245], v214 offset:128
	ds_read_b32 v255, v218
	s_nop 4
	v_mul_f32_e32 v204, v201, v201
	v_mul_f32_e32 v205, v203, v203
	v_fmac_f32_e32 v204, v200, v200
	v_fmac_f32_e32 v205, v202, v202
	v_add_f32_e32 v204, v204, v205
	v_mul_f32_e32 v205, v221, v221
	v_mul_f32_e32 v237, v223, v223
	v_fmac_f32_e32 v205, v220, v220
	v_fmac_f32_e32 v237, v222, v222
	v_add_f32_e32 v205, v205, v237
	v_add_f32_e32 v204, v204, v205
	v_mul_f32_e32 v205, v225, v225
	v_mul_f32_e32 v237, v227, v227
	v_fmac_f32_e32 v205, v224, v224
	v_fmac_f32_e32 v237, v226, v226
	v_add_f32_e32 v205, v205, v237
	v_add_f32_e32 v204, v204, v205
	v_mul_f32_e32 v205, v155, v155
	v_mul_f32_e32 v237, v157, v157
	v_fmac_f32_e32 v205, v154, v154
	v_fmac_f32_e32 v237, v156, v156
	v_add_f32_e32 v205, v205, v237
	v_add_f32_e32 v204, v204, v205
	v_mov_b32_e32 v205, v204
	v_cvt_pk_bf16_f32 v200, v200, v201
	v_cvt_pk_bf16_f32 v201, v202, v203
	v_permlane16_swap_b32_e32 v204, v205
	v_cvt_pk_bf16_f32 v202, v220, v221
	v_cvt_pk_bf16_f32 v203, v222, v223
	v_add_f32_e32 v204, v204, v205
	v_mov_b32_e32 v205, v204
	v_cvt_pk_bf16_f32 v220, v224, v225
	v_cvt_pk_bf16_f32 v221, v226, v227
	v_permlane32_swap_b32_e32 v204, v205
	v_cvt_pk_bf16_f32 v222, v154, v155
	v_cvt_pk_bf16_f32 v223, v156, v157
	v_add_f32_e32 v204, v204, v205
	s_waitcnt lgkmcnt(0)
	v_cndmask_b32_e64 v242, 0, v242, s[4:5]
	v_cndmask_b32_e64 v243, 0, v243, s[4:5]
	v_mfma_f32_16x16x32_bf16 v[238:241], v[174:177], v[200:203], 0
	v_cndmask_b32_e64 v244, 0, v244, s[4:5]
	v_cndmask_b32_e64 v245, 0, v245, s[4:5]
	v_mfma_f32_16x16x32_bf16 v[238:241], v[246:249], v[220:223], v[238:241]
	v_add_f32_e32 v255, v204, v255
	v_fmamk_f32 v255, v255, 0x3c2aaaab, v231
	v_mfma_f32_16x16x32_bf16 v[238:241], v[242:245], v[196:199], v[238:241]
	v_rsq_f32_e32 v255, v255
	s_add_i32 s50, s50, 16
	v_add_u32_e32 v218, 64, v218
	v_add_u32_e32 v217, 0x500, v217
	v_add_u32_e32 v216, 0x2100, v216
	v_mov_b32_e32 v178, v179
	v_mov_b32_e32 v179, v180
	v_mov_b32_e32 v180, v219
	v_mul_f32_e32 v200, v238, v255
	v_mul_f32_e32 v201, v239, v255
	v_mul_f32_e32 v202, v240, v255
	v_mul_f32_e32 v203, v241, v255
	s_nop 0
	v_permlane16_swap_b32_e32 v200, v201
	s_nop 0
	v_permlane16_swap_b32_e32 v202, v203
	s_nop 1
	v_permlane32_swap_b32_e32 v200, v202
	v_mov_b32_e32 v219, v200
	s_cmpk_eq_i32 s50, 0x50
	s_cbranch_scc0 .LBB0_1867
.LBB0_1869:
	s_waitcnt lgkmcnt(0)
	v_mov_b32_e32 v148, v178
	v_mov_b32_e32 v149, v179
	v_mov_b32_e32 v150, v180
	v_mov_b32_e32 v151, v219
	v_max_f32_e32 v146, v151, v151
	v_max_f32_e32 v147, v150, v150
	v_max_f32_e32 v146, v147, v146
	v_max3_f32 v146, v148, v149, v146
	s_nop 1
	v_mov_b32_dpp v147, v146 quad_perm:[1,0,3,2] row_mask:0xf bank_mask:0xf bound_ctrl:1
	v_max_f32_e32 v147, v147, v147
	v_max_f32_e32 v146, v146, v147
	s_nop 1
	v_mov_b32_dpp v147, v146 quad_perm:[2,3,0,1] row_mask:0xf bank_mask:0xf bound_ctrl:1
	v_max_f32_e32 v147, v147, v147
	v_max_f32_e32 v146, v146, v147
	s_nop 1
	v_mov_b32_dpp v147, v146 row_half_mirror row_mask:0xf bank_mask:0xf bound_ctrl:1
	v_max_f32_e32 v147, v147, v147
	v_max_f32_e32 v146, v146, v147
	s_nop 1
	v_mov_b32_dpp v147, v146 row_mirror row_mask:0xf bank_mask:0xf bound_ctrl:1
	v_max3_f32 v146, v213, v146, v147
	v_sub_f32_e32 v147, v148, v146
	v_exp_f32_e32 v147, v147
	v_sub_f32_e32 v148, v149, v146
	v_exp_f32_e32 v148, v148
	v_sub_f32_e32 v149, v150, v146
	v_bfe_u32 v150, v147, 16, 1
	v_exp_f32_e32 v149, v149
	v_add3_u32 v150, v147, v150, s74
	ds_write_b16_d16_hi v209, v150
	v_bfe_u32 v150, v148, 16, 1
	v_add3_u32 v150, v148, v150, s74
	ds_write_b16_d16_hi v209, v150 offset:32
	v_sub_f32_e32 v150, v151, v146
	v_bfe_u32 v153, v149, 16, 1
	v_exp_f32_e32 v150, v150
	v_sub_f32_e32 v152, v213, v146
	v_add3_u32 v151, v149, v153, s74
	ds_write_b16_d16_hi v209, v151 offset:64
	v_exp_f32_e32 v151, v152
	v_bfe_u32 v152, v150, 16, 1
	v_add3_u32 v152, v150, v152, s74
	ds_write_b16_d16_hi v209, v152 offset:96
	s_and_saveexec_b64 s[48:49], s[8:9]
	ds_write_b32 v210, v151
	s_or_b64 exec, exec, s[48:49]
	v_add_f32_e32 v147, 0, v147
	v_add_f32_e32 v147, v148, v147
	v_add_f32_e32 v147, v149, v147
	v_add_f32_e32 v148, v150, v147
	s_waitcnt lgkmcnt(0)
	v_add_u32_e32 v147, 0, v184
	s_barrier
	v_add_u32_e32 v147, 0x1cb00, v147
	v_fmac_f32_e32 v148, v212, v151
	ds_read_b128 v[150:153], v147
	ds_read_b128 v[154:157], v147 offset:64
	ds_read_b128 v[214:217], v211
	ds_read_b128 v[218:221], v211 offset:2304
	ds_read_b64_tr_b16 v[198:199], v186 offset:2112
	ds_read_b64_tr_b16 v[196:197], v186
	ds_read_b64_tr_b16 v[200:201], v186 offset:32
	ds_read_b64_tr_b16 v[202:203], v186 offset:2144
	ds_read_b128 v[222:225], v211 offset:64
	ds_read_b128 v[238:241], v211 offset:2368
	ds_read_b64_tr_b16 v[242:243], v186 offset:16896
	ds_read_b64_tr_b16 v[244:245], v186 offset:19008
	s_lshr_b32 s81, s78, 3
	s_cmp_lg_u32 s47, 7
	s_cselect_b64 s[48:49], -1, 0
	s_and_b64 vcc, exec, s[48:49]
	s_waitcnt lgkmcnt(11)
	v_pk_mul_f32 v[134:135], v[134:135], v[150:151]
	v_pk_mul_f32 v[136:137], v[136:137], v[152:153]
	v_pk_mul_f32 v[142:143], v[142:143], v[150:151]
	v_pk_mul_f32 v[144:145], v[144:145], v[152:153]
	ds_read_b64_tr_b16 v[150:151], v186 offset:16928
	ds_read_b64_tr_b16 v[152:153], v186 offset:19040
	s_waitcnt lgkmcnt(12)
	v_pk_mul_f32 v[130:131], v[130:131], v[154:155]
	v_pk_mul_f32 v[132:133], v[132:133], v[156:157]
	v_pk_mul_f32 v[138:139], v[138:139], v[154:155]
	v_pk_mul_f32 v[140:141], v[140:141], v[156:157]
	s_waitcnt lgkmcnt(8)
	v_mfma_f32_16x16x32_bf16 v[134:137], v[214:217], v[196:199], v[134:137]
	v_mfma_f32_16x16x32_bf16 v[130:133], v[218:221], v[196:199], v[130:133]
	s_waitcnt lgkmcnt(6)
	v_mfma_f32_16x16x32_bf16 v[142:145], v[214:217], v[200:203], v[142:145]
	v_mfma_f32_16x16x32_bf16 v[138:141], v[218:221], v[200:203], v[138:141]
	s_waitcnt lgkmcnt(2)
	v_mfma_f32_16x16x32_bf16 v[134:137], v[222:225], v[242:245], v[134:137]
	v_mfma_f32_16x16x32_bf16 v[130:133], v[238:241], v[242:245], v[130:133]
	s_waitcnt lgkmcnt(0)
	v_mfma_f32_16x16x32_bf16 v[142:145], v[222:225], v[150:153], v[142:145]
	v_mfma_f32_16x16x32_bf16 v[138:141], v[238:241], v[150:153], v[138:141]
	s_cbranch_vccnz .LBB0_1875
	s_mul_i32 s47, s81, s24
	s_add_i32 s50, s47, s25
	s_ashr_i32 s51, s50, 31
	s_lshl_b64 s[52:53], s[50:51], 15
	v_mov_b32_e32 v151, s53
	v_or_b32_e32 v150, s52, v168
	v_lshl_add_u64 v[152:153], v[162:163], 0, v[150:151]
	global_store_dword v[152:153], v134, off
	global_store_dword v[152:153], v135, off offset:1024
	global_store_dword v[152:153], v136, off offset:2048
	global_store_dword v[152:153], v137, off offset:3072
	global_store_dword v[152:153], v142, off offset:64
	global_store_dword v[152:153], v143, off offset:1088
	global_store_dword v[152:153], v144, off offset:2112
	global_store_dword v[152:153], v145, off offset:3136
	v_or_b32_e32 v152, 0x4000, v150
	v_mov_b32_e32 v153, s53
	v_lshl_add_u64 v[154:155], v[162:163], 0, v[152:153]
	global_store_dword v[154:155], v130, off
	v_or_b32_e32 v154, 0x4400, v150
	v_mov_b32_e32 v155, s53
	v_lshl_add_u64 v[156:157], v[162:163], 0, v[154:155]
	v_add_f32_dpp v147, v148, v148 quad_perm:[1,0,3,2] row_mask:0xf bank_mask:0xf bound_ctrl:1
	global_store_dword v[156:157], v131, off
	v_or_b32_e32 v156, 0x4800, v150
	v_mov_b32_e32 v157, s53
	v_lshl_add_u64 v[152:153], v[164:165], 0, v[152:153]
	v_add_f32_dpp v147, v147, v147 quad_perm:[2,3,0,1] row_mask:0xf bank_mask:0xf bound_ctrl:1
	v_lshl_add_u64 v[196:197], v[162:163], 0, v[156:157]
	v_or_b32_e32 v150, 0x4c00, v150
	global_store_dword v[152:153], v138, off
	v_lshl_add_u64 v[152:153], v[164:165], 0, v[154:155]
	v_add_f32_dpp v147, v147, v147 row_half_mirror row_mask:0xf bank_mask:0xf bound_ctrl:1
	global_store_dword v[196:197], v132, off
	v_lshl_add_u64 v[196:197], v[162:163], 0, v[150:151]
	global_store_dword v[152:153], v139, off
	v_lshl_add_u64 v[152:153], v[164:165], 0, v[156:157]
	v_lshl_add_u64 v[150:151], v[164:165], 0, v[150:151]
	v_mov_b32_dpp v149, v147 row_mirror row_mask:0xf bank_mask:0xf bound_ctrl:1
	global_store_dword v[196:197], v133, off
	global_store_dword v[152:153], v140, off
	global_store_dword v[150:151], v141, off
	s_and_saveexec_b64 s[52:53], s[8:9]
	s_cbranch_execz .LBB0_1874
	s_lshl_b64 s[50:51], s[50:51], 8
	v_lshl_add_u64 v[150:151], v[166:167], 0, s[50:51]
	v_add_f32_e32 v147, v147, v149
	global_store_dwordx2 v[150:151], v[146:147], off
